# v020 with GQA start stagger regrouped: 8 ring positions (u>>5)<<18 so 4 co-resident WGs per XCD share K/V tiles in L2, instead of 32 distinct positions
# speedup vs baseline: 1.0068x; 1.0068x over previous
; template <bool NA, int ROWB>
; __device__ __forceinline__ void attn_dma(const bf16* __restrict__ Qb, const bf16* __restrict__ Kh, const bf16* __restrict__ Vh, bf16* __restrict__ Ob, int NT, char* lds, const int tid, float* __restrict__ ssb, int qrow0, int kr_lo, const float* bl) {
;   const int wid = tid >> 6, lane = tid & 63, r32 = lane & 31, hi = lane >> 5;
;   const int wid_s = __builtin_amdgcn_readfirstlane(wid);
;   char* V_lds = lds; char* K_lds = lds + 3 * SHM_V;
;   float* li_l = (float*)(lds + 3 * SHM_V + 3 * SHM_K) + wid * 64;
;   float* al_l = li_l + 32;
;   float m_reg = -1e30f, l_reg = 0; f32x16 o[4] = {}; bf16x8 qr[8];
;   const int qrow = qrow0 + (wid >> 1), qc = 32 * (wid & 1) + r32;
;   const int c0 = min(max(qc - 8, 0), 48), r0 = min(max(qrow - 4, 0), 120);
;   const bf16* Qw = Qb + (long)(wid * QBLK + r32) * LDQ + hi * 8;
; #pragma unroll
;   for (int d0 = 0; d0 < 8; ++d0) qr[d0] = *reinterpret_cast<const bf16x8*>(Qw + d0 * 16);
;   const int vb0 = (int)(uintptr_t)V_lds + v_rd_base(lane);
;   auto src_off = [&](int i, unsigned& ko, unsigned& vo) __attribute__((always_inline)) {
;     const int b = (wid * 2 + i) * 1024 + lane * 16;
;     { const int row = b >> 8, cb = (b & 255) ^ ((row & 7) << 4); ko = (unsigned)(row * ROWB + cb); }
; __global__ void __launch_bounds__(512, 2) fwd_megakernel(Args a) {
;     ...
;                 const int kr_lo = max(0, 4 * blk - 4), NT = min(12, 128 - kr_lo);
;                 att::attn_dma<true, 9216>(Hb + (size_t)(blk * 256) * DIN + h * 128, Hb + (size_t)(kr_lo * 64) * DIN + 1024 + h * 128, Hb + (size_t)(kr_lo * 64) * DIN + 2048 + h * 128,
;                                           OB + (size_t)(blk * 256) * DM + h * 128, NT, (char*)lds, tid, (float*)(ws + OFF_SS) + (size_t)(blk * 256) * 16 + h, 4 * blk, kr_lo, bl);
;             }
;         } else if (kind == 5 && (PHMASK & 64)) {
;             for (int u = blockIdx.x; u < 256; u += G) {
;                 const int h = u & 7, qb = u >> 3;
;                 __syncthreads();
;                 att::attn_dma<false, 256>(Hb + (size_t)(qb * 256) * DIN + 3072 + h * 128, KC + (size_t)(h >> 2) * SEQ * 128, VC + (size_t)(h >> 2) * SEQ * 128,
;                                 OB + (size_t)(qb * 256) * DM + 1024 + h * 128, 128, (char*)lds, tid, (float*)(ws + OFF_SS) + (size_t)(qb * 256) * 16 + 8 + h, 0, 0, nullptr);
.LBB0_105:
	s_lshl_b32 s0, s22, 19
	s_and_b32 s0, s0, 0x200000
	v_readlane_b32 s4, v254, 32
	v_readlane_b32 s5, v254, 33
	s_add_u32 s18, s4, s0
	s_addc_u32 s19, s5, 0
	s_lshl_b32 s0, s23, 5
	s_and_b32 s6, s0, 0xffffff00
	s_and_b32 s14, s23, 7
	s_ashr_i32 s7, s6, 31
	s_mul_i32 s1, s6, 0x2400
	s_mul_hi_i32 s0, s6, 0x2400
	s_add_u32 s1, s16, s1
	s_addc_u32 s4, s17, s0
	s_lshl_b32 s15, s14, 7
	s_lshl_b32 s0, s14, 8
	s_add_u32 s0, s1, s0
	s_addc_u32 s1, s4, 0
	s_waitcnt lgkmcnt(0)
	v_lshl_add_u64 v[0:1], s[0:1], 0, v[162:163]
	v_mov_b32_e32 v175, v113
	v_lshl_add_u64 v[0:1], v[0:1], 0, v[174:175]
	s_movk_i32 s0, 0x1000
	v_add_co_u32_e64 v2, s[4:5], s0, v0
	s_nop 1
	v_addc_co_u32_e64 v3, s[4:5], 0, v1, s[4:5]
	s_barrier
	global_load_dwordx4 v[138:141], v[2:3], off offset:2048
	s_mov_b64 s[4:5], 0x1800
	v_lshl_add_u64 v[0:1], v[0:1], 0, s[4:5]
	global_load_dwordx4 v[142:145], v[0:1], off offset:32
	global_load_dwordx4 v[134:137], v[0:1], off offset:64
	global_load_dwordx4 v[114:117], v[0:1], off offset:96
	global_load_dwordx4 v[118:121], v[0:1], off offset:128
	global_load_dwordx4 v[122:125], v[0:1], off offset:160
	global_load_dwordx4 v[126:129], v[0:1], off offset:192
	global_load_dwordx4 v[130:133], v[0:1], off offset:224
	s_lshl_b32 s0, s23, 19
	s_and_b32 s16, s0, 0x200000
	s_add_u32 s0, s12, s16
	s_addc_u32 s1, s13, 0
	s_add_u32 s16, s8, s16
	v_readfirstlane_b32 s4, v184
	s_addc_u32 s17, s9, 0
	s_lshr_b32 s98, s23, 5
	s_lshl_b32 s98, s98, 18
	s_add_u32 s0, s0, s98
	s_addc_u32 s1, s1, 0
	s_add_u32 s16, s16, s98
	s_addc_u32 s17, s17, 0
	s_lshl_b32 s4, s4, 11
	s_add_i32 s5, s4, 0
	v_lshl_add_u64 v[0:1], s[0:1], 0, v[164:165]
	s_add_i32 m0, s5, 0xc000
	v_add_u32_e32 v4, 0, v187
	global_load_lds_dwordx4 v[0:1], off
	v_lshl_add_u64 v[0:1], s[16:17], 0, v[166:167]
	s_mov_b32 m0, s5
	v_add_u32_e32 v8, 0, v188
	global_load_lds_dwordx4 v[0:1], off
	v_lshl_add_u64 v[0:1], s[0:1], 0, v[168:169]
	s_add_i32 m0, s5, 0xc400
	v_add_u32_e32 v12, 0, v194
	global_load_lds_dwordx4 v[0:1], off
	s_add_i32 m0, s5, 0x400
	s_add_u32 s0, s0, 0x4000
	s_addc_u32 s1, s1, 0
	v_lshl_add_u64 v[0:1], s[16:17], 0, v[170:171]
	s_add_u32 s16, s16, 0x4000
	global_load_lds_dwordx4 v[0:1], off
	s_addc_u32 s17, s17, 0
	v_lshl_add_u64 v[0:1], s[0:1], 0, v[164:165]
	s_add_i32 m0, s5, 0x10000
	v_mov_b32_e32 v112, 0
	global_load_lds_dwordx4 v[0:1], off
	v_lshl_add_u64 v[0:1], s[16:17], 0, v[166:167]
	s_add_i32 m0, s5, 0x4000
	s_mov_b32 s38, s36
	global_load_lds_dwordx4 v[0:1], off
	v_lshl_add_u64 v[0:1], s[0:1], 0, v[168:169]
	s_add_i32 m0, s5, 0x10400
	s_mov_b32 s0, 1
	global_load_lds_dwordx4 v[0:1], off
	v_lshl_add_u64 v[0:1], s[16:17], 0, v[170:171]
	s_add_i32 m0, s5, 0x4400
	s_mov_b32 s24, 0
	global_load_lds_dwordx4 v[0:1], off
	s_waitcnt vmcnt(0)
	s_waitcnt vmcnt(0) lgkmcnt(0)
	s_barrier
; #define NAM(P0, P1, t) do { if constexpr (NA) na_mask(P0, P1, kr_lo + (t), r0, qrow, qc, c0, hi, bl); } while (0)
; #define PSM(P0, P1, MN, AL) do { if constexpr (NA) partialSM(P0, P1, m_reg, MN, AL); else { AL = 1.f; _Pragma("unroll") for (int r = 0; r < 16; ++r) P0[r] = __builtin_amdgcn_exp2f(P0[r]); } } while (0)
; #define VM0() asm volatile("s_waitcnt vmcnt(0)" ::: "memory")
; #define NAM(P0, P1, t) do { if constexpr (NA) na_mask(P0, P1, kr_lo + (t), r0, qrow, qc, c0, hi, bl); } while (0)
; #define PSM(P0, P1, MN, AL) do { if constexpr (NA) partialSM(P0, P1, m_reg, MN, AL); else { AL = 1.f; _Pragma("unroll") for (int r = 0; r < 16; ++r) P0[r] = __builtin_amdgcn_exp2f(P0[r]); } } while (0)
; template <bool QL>
; __device__ __forceinline__ void qkt(f32x16& p0, f32x16& p1, const bf16* Ks, const bf16x8* qr, const char* ql, int r32, int hi) {
;   p0 = f32x16{}; p1 = f32x16{};
;   for (int d0 = 0; d0 < 8; ++d0) { int cb = (d0 * 16 + hi * 8) * 2;
;     bf16x8 b0 = *reinterpret_cast<const bf16x8*>((const char*)Ks + KSWZ(r32, cb));
;     bf16x8 b1 = *reinterpret_cast<const bf16x8*>((const char*)Ks + KSWZ(32 + r32, cb));
;     bf16x8 q; if constexpr (QL) q = *reinterpret_cast<const bf16x8*>(ql + d0 * 1024); else q = qr[d0];
;     p0 = __builtin_amdgcn_mfma_f32_32x32x16_bf16(b0, q, p0, 0, 0, 0);
;     p1 = __builtin_amdgcn_mfma_f32_32x32x16_bf16(b1, q, p1, 0, 0, 0); }
; }
; template <bool NA, int ROWB>
; __device__ __forceinline__ void attn_dma(const bf16* __restrict__ Qb, const bf16* __restrict__ Kh, const bf16* __restrict__ Vh, bf16* __restrict__ Ob, int NT, char* lds, const int tid, float* __restrict__ ssb, int qrow0, int kr_lo, const float* bl) {
;     ...
;   float m_reg = -1e30f, l_reg = 0; f32x16 o[4] = {}; bf16x8 qr[8];
;     ...
;   f32x16 pA0, pA1, pB0, pB1; bf16x8 pa0, pa1, pa2, pa3; float mnA, mnB, alA, alB;
;   DMA_TILE(0, 0); DMA_TILE(1, 1); VM0(); __syncthreads();
;   qkt<false>(pA0, pA1, (const bf16*)K_lds, qr, nullptr, r32, hi); NAM(pA0, pA1, 0); PSM(pA0, pA1, mnA, alA);
;   int bp = 0, bc = 1, bn = 2;
	ds_read_b128 v[0:3], v4 offset:49152
	ds_read_b128 v[4:7], v4 offset:57344
	s_mov_b32 s17, 2
	s_mov_b32 s16, -1
	v_mov_b32_e32 v13, v112
	s_waitcnt lgkmcnt(1)
	v_mfma_f32_32x32x16_bf16 v[14:29], v[0:3], v[138:141], 0
	v_mov_b32_e32 v34, v112
	v_mov_b32_e32 v35, v112
	v_mov_b32_e32 v36, v112
	v_mov_b32_e32 v37, v112
	v_mov_b32_e32 v38, v112
	v_mov_b32_e32 v39, v112
	v_mov_b32_e32 v40, v112
	s_waitcnt lgkmcnt(0)
	v_mfma_f32_32x32x16_bf16 v[64:79], v[4:7], v[138:141], 0
	ds_read_b128 v[0:3], v8 offset:49152
	ds_read_b128 v[4:7], v8 offset:57344
	v_add_u32_e32 v8, 0, v189
	v_mov_b32_e32 v41, v112
	v_mov_b32_e32 v42, v112
	v_mov_b32_e32 v43, v112
	v_mov_b32_e32 v44, v112
	v_mov_b32_e32 v45, v112
	s_waitcnt lgkmcnt(1)
	v_mfma_f32_32x32x16_bf16 v[14:29], v[0:3], v[142:145], v[14:29]
	v_mov_b32_e32 v46, v112
	v_mov_b32_e32 v47, v112
	v_mov_b32_e32 v48, 0
	v_mov_b32_e32 v49, v112
	v_mov_b32_e32 v50, v112
	v_mov_b32_e32 v51, v112
	v_mov_b32_e32 v52, v112
	s_waitcnt lgkmcnt(0)
	v_mfma_f32_32x32x16_bf16 v[64:79], v[4:7], v[142:145], v[64:79]
	ds_read_b128 v[0:3], v8 offset:49152
	ds_read_b128 v[4:7], v8 offset:57344
	v_add_u32_e32 v8, 0, v190
	v_mov_b32_e32 v53, v112
	v_mov_b32_e32 v54, v112
	v_mov_b32_e32 v55, v112
	v_mov_b32_e32 v56, v112
	v_mov_b32_e32 v57, v112
	s_waitcnt lgkmcnt(1)
	v_mfma_f32_32x32x16_bf16 v[14:29], v[0:3], v[134:137], v[14:29]
	v_mov_b32_e32 v58, v112
	v_mov_b32_e32 v59, v112
	v_mov_b32_e32 v60, v112
	v_mov_b32_e32 v61, v112
	v_mov_b32_e32 v62, v112
	v_mov_b32_e32 v63, v112
	s_mov_b64 s[28:29], 0x25d48000
	s_waitcnt lgkmcnt(0)
	v_mfma_f32_32x32x16_bf16 v[64:79], v[4:7], v[134:137], v[64:79]
	ds_read_b128 v[0:3], v8 offset:49152
	ds_read_b128 v[4:7], v8 offset:57344
	v_add_u32_e32 v8, 0, v191
	s_mov_b64 s[36:37], 0x26148000
	s_mov_b64 s[40:41], 0x25d4c000
	s_mov_b64 s[42:43], 0x2614c000
	s_waitcnt lgkmcnt(1)
	v_mfma_f32_32x32x16_bf16 v[14:29], v[0:3], v[114:117], v[14:29]
	s_waitcnt lgkmcnt(0)
	v_mfma_f32_32x32x16_bf16 v[64:79], v[4:7], v[114:117], v[64:79]
	ds_read_b128 v[0:3], v8 offset:49152
	ds_read_b128 v[4:7], v8 offset:57344
	v_add_u32_e32 v8, 0, v192
	s_waitcnt lgkmcnt(1)
	v_mfma_f32_32x32x16_bf16 v[14:29], v[0:3], v[118:121], v[14:29]
	s_waitcnt lgkmcnt(0)
	v_mfma_f32_32x32x16_bf16 v[64:79], v[4:7], v[118:121], v[64:79]
	ds_read_b128 v[0:3], v8 offset:49152
	ds_read_b128 v[4:7], v8 offset:57344
	v_add_u32_e32 v8, 0, v193
	s_waitcnt lgkmcnt(1)
	v_mfma_f32_32x32x16_bf16 v[14:29], v[0:3], v[122:125], v[14:29]
	s_waitcnt lgkmcnt(0)
	v_mfma_f32_32x32x16_bf16 v[64:79], v[4:7], v[122:125], v[64:79]
	ds_read_b128 v[0:3], v8 offset:49152
	ds_read_b128 v[4:7], v8 offset:57344
	ds_read_b128 v[8:11], v12 offset:49152
	ds_read_b128 v[30:33], v12 offset:57344
	v_mov_b32_e32 v12, v112
	s_waitcnt lgkmcnt(3)
	v_mfma_f32_32x32x16_bf16 v[14:29], v[0:3], v[126:129], v[14:29]
	v_mov_b32_e32 v0, 0
	v_mov_b32_e32 v1, v112
	v_mov_b32_e32 v2, v112
	v_mov_b32_e32 v3, v112
	s_waitcnt lgkmcnt(2)
	v_mfma_f32_32x32x16_bf16 v[64:79], v[4:7], v[126:129], v[64:79]
	v_mov_b32_e32 v4, v112
	v_mov_b32_e32 v5, v112
	v_mov_b32_e32 v6, v112
	v_mov_b32_e32 v7, v112
	s_waitcnt lgkmcnt(1)
	v_mfma_f32_32x32x16_bf16 v[14:29], v[8:11], v[130:133], v[14:29]
	v_mov_b32_e32 v8, v112
	v_mov_b32_e32 v9, v112
	v_mov_b32_e32 v10, v112
	v_mov_b32_e32 v11, v112
	s_waitcnt lgkmcnt(0)
	v_mfma_f32_32x32x16_bf16 v[64:79], v[30:33], v[130:133], v[64:79]
	s_nop 5
	v_exp_f32_e32 v212, v14
	v_exp_f32_e32 v214, v15
	v_exp_f32_e32 v210, v16
	v_exp_f32_e32 v213, v17
	v_exp_f32_e32 v208, v18
	v_exp_f32_e32 v211, v19
	v_exp_f32_e32 v207, v20
	v_exp_f32_e32 v209, v21
	v_exp_f32_e32 v203, v22
	v_exp_f32_e32 v206, v23
	v_exp_f32_e32 v198, v24
	v_exp_f32_e32 v205, v25
	v_exp_f32_e32 v196, v26
	v_exp_f32_e32 v199, v27
	v_exp_f32_e32 v175, v28
	v_exp_f32_e32 v197, v29
	v_mov_b32_e32 v14, v112
	v_mov_b32_e32 v15, v112
	v_mov_b32_e32 v16, 0
	v_mov_b32_e32 v17, v112
	v_mov_b32_e32 v18, v112
	v_mov_b32_e32 v19, v112
	v_mov_b32_e32 v20, v112
	v_mov_b32_e32 v21, v112
	v_mov_b32_e32 v22, v112
	v_mov_b32_e32 v23, v112
	v_mov_b32_e32 v24, v112
	v_mov_b32_e32 v25, v112
	v_mov_b32_e32 v26, v112
	v_mov_b32_e32 v27, v112
	v_mov_b32_e32 v28, v112
	v_mov_b32_e32 v29, v112
	v_mov_b32_e32 v30, v112
	v_mov_b32_e32 v31, v112
	v_mov_b32_e32 v32, 0
	v_mov_b32_e32 v33, v112
	s_mov_b32 s24, 0
	s_mov_b32 s0, 0x4000
	s_mov_b32 s17, 0x8000
	s_add_u32 s40, s18, s28
	s_addc_u32 s41, s19, s29
	s_sub_u32 s40, s40, 0x8000
	s_subb_u32 s41, s41, 0
	s_add_u32 s42, s18, s36
	s_addc_u32 s43, s19, s37
	s_sub_u32 s42, s42, 0x8000
	s_subb_u32 s43, s43, 0
	s_add_u32 s18, s98, 0x8000
	s_mov_b32 s16, 0
	s_cmp_ge_u32 s4, 0x2000
	s_cbranch_scc0 .Lgqa_lead
	s_barrier
